# RG-LRU chunk: conv + B-operand packing rewritten with software-pipelined LDS reads, and the 32 gate-MFMA fragment reads pipelined 8 deep (counted lgkmcnt) instead of a wait before almost every tap / M
# speedup vs baseline: 1.0134x; 1.0002x over previous
; __device__ __forceinline__ unsigned cvt_pk_bf16(float lo, float hi) { unsigned r; asm volatile("v_cvt_pk_bf16_f32 %0, %1, %2" : "=v"(r) : "v"(lo), "v"(hi)); return r; }
; __device__ __forceinline__ float bf_lo(unsigned w) { return __uint_as_float(w << 16); }
; __device__ __forceinline__ float bf_hi(unsigned w) { return __uint_as_float(w & 0xffff0000u); }
; #define LAS __attribute__((address_space(3)))
; __device__ __forceinline__ void lru_item(const Frame& F, const bf16* XR, bf16* XGYL, const float* conv_w, const float* conv_b, const float* wa, const float* ba, const float* wx, const float* bx, const float* lam, int b, int hh, int j2) {
;     ...
;         for (int ks = 0; ks < 4; ++ks) { const int cl = 32 * ks + 8 * g; float a8[8];
;             { const f32x4 b0 = *(const LAS f32x4*)(tab + 512 + cl), b1 = *(const LAS f32x4*)(tab + 512 + cl + 4); a8[0] = b0[0]; a8[1] = b0[1]; a8[2] = b0[2]; a8[3] = b0[3]; a8[4] = b1[0]; a8[5] = b1[1]; a8[6] = b1[2]; a8[7] = b1[3]; }
; #pragma unroll
;             for (int k = 0; k < 4; ++k) { const int rr = 16 * w + tl + k; v4u xq = *(const LAS v4u*)(xb + k * 256 + (((4 * ks + g) ^ (rr & 15)) << 4));
;                 const bool inb = (chunk > 0) || (rr >= 3); xq.x = inb ? xq.x : 0u; xq.y = inb ? xq.y : 0u; xq.z = inb ? xq.z : 0u; xq.w = inb ? xq.w : 0u;
;                 const f32x4 w0 = *(const LAS f32x4*)(tab + k * 128 + cl), w1 = *(const LAS f32x4*)(tab + k * 128 + cl + 4);
;                 a8[0] += w0[0] * pg8::bf_lo(xq.x); a8[1] += w0[1] * pg8::bf_hi(xq.x); a8[2] += w0[2] * pg8::bf_lo(xq.y); a8[3] += w0[3] * pg8::bf_hi(xq.y);
;                 a8[4] += w1[0] * pg8::bf_lo(xq.z); a8[5] += w1[1] * pg8::bf_hi(xq.z); a8[6] += w1[2] * pg8::bf_lo(xq.w); a8[7] += w1[3] * pg8::bf_hi(xq.w); }
;             v4u u4; u4.x = pg8::cvt_pk_bf16(a8[0], a8[1]); u4.y = pg8::cvt_pk_bf16(a8[2], a8[3]); u4.z = pg8::cvt_pk_bf16(a8[4], a8[5]); u4.w = pg8::cvt_pk_bf16(a8[6], a8[7]); bfr[ks] = __builtin_bit_cast(bf16x8, u4);
.LBB0_346:
	s_add_i32 s44, s6, -1
	s_and_b32 s7, s44, 1
	s_mul_i32 s2, s7, 0x9000
	v_add_u32_e32 v28, s2, v134
	v_add_u32_e32 v0, v28, v116
	global_load_dwordx4 v[8:11], v[106:107], off offset:-64
	global_load_dwordx4 v[4:7], v[106:107], off
	s_cmp_lg_u32 s95, 0
	s_cselect_b64 s[2:3], -1, 0
	s_or_b64 vcc, s[12:13], s[2:3]
	s_or_b64 s[46:47], s[14:15], s[2:3]
	v_or_b32_e32 v248, s44, v88
	v_cmp_eq_u32_e64 s[44:45], 0, v248
	v_add_u32_e32 v250, v28, v116
	v_add_u32_e32 v251, v28, v117
	ds_read_b128 v[188:191], v115 offset:2048
	ds_read_b128 v[192:195], v115 offset:2064
	ds_read_b128 v[196:199], v250 offset:45056
	ds_read_b128 v[200:203], v251 offset:45312
	ds_read_b128 v[204:207], v115
	ds_read_b128 v[208:211], v115 offset:16
	ds_read_b128 v[212:215], v115 offset:512
	ds_read_b128 v[216:219], v115 offset:528
	v_add_u32_e32 v250, v28, v118
	v_add_u32_e32 v251, v28, v119
	ds_read_b128 v[220:223], v250 offset:45568
	ds_read_b128 v[224:227], v251 offset:45824
	ds_read_b128 v[228:231], v115 offset:1024
	ds_read_b128 v[236:239], v115 offset:1040
	ds_read_b128 v[240:243], v115 offset:1536
	ds_read_b128 v[244:247], v115 offset:1552
	s_waitcnt lgkmcnt(6)
	v_cndmask_b32_e32 v196, 0, v196, vcc
	v_cndmask_b32_e32 v197, 0, v197, vcc
	v_cndmask_b32_e32 v198, 0, v198, vcc
	v_cndmask_b32_e32 v199, 0, v199, vcc
	v_lshlrev_b32_e32 v248, 16, v196
	v_lshlrev_b32_e32 v249, 16, v197
	v_lshlrev_b32_e32 v250, 16, v198
	v_lshlrev_b32_e32 v251, 16, v199
	v_and_b32_e32 v196, 0xffff0000, v196
	v_and_b32_e32 v197, 0xffff0000, v197
	v_and_b32_e32 v198, 0xffff0000, v198
	v_and_b32_e32 v199, 0xffff0000, v199
	v_fma_f32 v0, v204, v248, v188
	v_fma_f32 v1, v205, v196, v189
	v_fma_f32 v2, v206, v249, v190
	v_fma_f32 v93, v207, v197, v191
	v_fma_f32 v95, v208, v250, v192
	v_fma_f32 v140, v209, v198, v193
	v_fma_f32 v141, v210, v251, v194
	v_fma_f32 v142, v211, v199, v195
	v_cndmask_b32_e64 v200, 0, v200, s[46:47]
	v_cndmask_b32_e64 v201, 0, v201, s[46:47]
	v_cndmask_b32_e64 v202, 0, v202, s[46:47]
	v_cndmask_b32_e64 v203, 0, v203, s[46:47]
	v_lshlrev_b32_e32 v248, 16, v200
	v_lshlrev_b32_e32 v249, 16, v201
	v_lshlrev_b32_e32 v250, 16, v202
	v_lshlrev_b32_e32 v251, 16, v203
	v_and_b32_e32 v200, 0xffff0000, v200
	v_and_b32_e32 v201, 0xffff0000, v201
	v_and_b32_e32 v202, 0xffff0000, v202
	v_and_b32_e32 v203, 0xffff0000, v203
	v_fmac_f32_e32 v0, v212, v248
	v_fmac_f32_e32 v1, v213, v200
	v_fmac_f32_e32 v2, v214, v249
	v_fmac_f32_e32 v93, v215, v201
	v_fmac_f32_e32 v95, v216, v250
	v_fmac_f32_e32 v140, v217, v202
	v_fmac_f32_e32 v141, v218, v251
	v_fmac_f32_e32 v142, v219, v203
	v_add_u32_e32 v250, v28, v120
	v_add_u32_e32 v251, v28, v121
	ds_read_b128 v[188:191], v115 offset:2176
	ds_read_b128 v[192:195], v115 offset:2192
	ds_read_b128 v[196:199], v250 offset:45056
	ds_read_b128 v[200:203], v251 offset:45312
	ds_read_b128 v[204:207], v115 offset:128
	ds_read_b128 v[208:211], v115 offset:144
	ds_read_b128 v[212:215], v115 offset:640
	ds_read_b128 v[216:219], v115 offset:656
	s_waitcnt lgkmcnt(8)
	v_cndmask_b32_e64 v220, v220, 0, s[44:45]
	v_cndmask_b32_e64 v221, v221, 0, s[44:45]
	v_cndmask_b32_e64 v222, v222, 0, s[44:45]
	v_cndmask_b32_e64 v223, v223, 0, s[44:45]
	v_lshlrev_b32_e32 v248, 16, v220
	v_lshlrev_b32_e32 v249, 16, v221
	v_lshlrev_b32_e32 v250, 16, v222
	v_lshlrev_b32_e32 v251, 16, v223
	v_and_b32_e32 v220, 0xffff0000, v220
	v_and_b32_e32 v221, 0xffff0000, v221
	v_and_b32_e32 v222, 0xffff0000, v222
	v_and_b32_e32 v223, 0xffff0000, v223
	v_mul_f32_e32 v228, v228, v248
	v_mul_f32_e32 v229, v229, v220
	v_mul_f32_e32 v230, v230, v249
	v_mul_f32_e32 v231, v231, v221
	v_mul_f32_e32 v236, v236, v250
	v_mul_f32_e32 v237, v237, v222
	v_mul_f32_e32 v238, v238, v251
	v_mul_f32_e32 v239, v239, v223
	v_lshlrev_b32_e32 v248, 16, v224
	v_lshlrev_b32_e32 v249, 16, v225
	v_lshlrev_b32_e32 v250, 16, v226
	v_lshlrev_b32_e32 v251, 16, v227
	v_and_b32_e32 v224, 0xffff0000, v224
	v_and_b32_e32 v225, 0xffff0000, v225
	v_and_b32_e32 v226, 0xffff0000, v226
	v_and_b32_e32 v227, 0xffff0000, v227
	v_mul_f32_e32 v240, v240, v248
	v_mul_f32_e32 v241, v241, v224
	v_mul_f32_e32 v242, v242, v249
	v_mul_f32_e32 v243, v243, v225
	v_mul_f32_e32 v244, v244, v250
	v_mul_f32_e32 v245, v245, v226
	v_mul_f32_e32 v246, v246, v251
	v_mul_f32_e32 v247, v247, v227
	v_add_f32_e32 v0, v0, v228
	v_add_f32_e32 v1, v1, v229
	v_add_f32_e32 v2, v2, v230
	v_add_f32_e32 v93, v93, v231
	v_add_f32_e32 v95, v95, v236
	v_add_f32_e32 v140, v140, v237
	v_add_f32_e32 v141, v141, v238
	v_add_f32_e32 v142, v142, v239
	v_add_f32_e32 v0, v0, v240
	v_add_f32_e32 v1, v1, v241
	v_add_f32_e32 v2, v2, v242
	v_add_f32_e32 v93, v93, v243
	v_add_f32_e32 v95, v95, v244
	v_add_f32_e32 v140, v140, v245
	v_add_f32_e32 v141, v141, v246
	v_add_f32_e32 v142, v142, v247
	v_add_u32_e32 v250, v28, v122
	v_add_u32_e32 v251, v28, v123
	ds_read_b128 v[220:223], v250 offset:45568
	ds_read_b128 v[224:227], v251 offset:45824
	ds_read_b128 v[228:231], v115 offset:1152
	ds_read_b128 v[236:239], v115 offset:1168
	ds_read_b128 v[240:243], v115 offset:1664
	ds_read_b128 v[244:247], v115 offset:1680
	v_cvt_pk_bf16_f32 v12, v0, v1
	v_cvt_pk_bf16_f32 v13, v2, v93
	v_cvt_pk_bf16_f32 v14, v95, v140
	v_cvt_pk_bf16_f32 v15, v141, v142
	s_waitcnt lgkmcnt(6)
; __device__ __forceinline__ unsigned cvt_pk_bf16(float lo, float hi) { unsigned r; asm volatile("v_cvt_pk_bf16_f32 %0, %1, %2" : "=v"(r) : "v"(lo), "v"(hi)); return r; }
; __device__ __forceinline__ float bf_lo(unsigned w) { return __uint_as_float(w << 16); }
; __device__ __forceinline__ float bf_hi(unsigned w) { return __uint_as_float(w & 0xffff0000u); }
; #define LAS __attribute__((address_space(3)))
; __device__ __forceinline__ void lru_item(const Frame& F, const bf16* XR, bf16* XGYL, const float* conv_w, const float* conv_b, const float* wa, const float* ba, const float* wx, const float* bx, const float* lam, int b, int hh, int j2) {
;     ...
;         for (int ks = 0; ks < 4; ++ks) { const int cl = 32 * ks + 8 * g; float a8[8];
;             { const f32x4 b0 = *(const LAS f32x4*)(tab + 512 + cl), b1 = *(const LAS f32x4*)(tab + 512 + cl + 4); a8[0] = b0[0]; a8[1] = b0[1]; a8[2] = b0[2]; a8[3] = b0[3]; a8[4] = b1[0]; a8[5] = b1[1]; a8[6] = b1[2]; a8[7] = b1[3]; }
; #pragma unroll
;             for (int k = 0; k < 4; ++k) { const int rr = 16 * w + tl + k; v4u xq = *(const LAS v4u*)(xb + k * 256 + (((4 * ks + g) ^ (rr & 15)) << 4));
;                 const bool inb = (chunk > 0) || (rr >= 3); xq.x = inb ? xq.x : 0u; xq.y = inb ? xq.y : 0u; xq.z = inb ? xq.z : 0u; xq.w = inb ? xq.w : 0u;
;                 const f32x4 w0 = *(const LAS f32x4*)(tab + k * 128 + cl), w1 = *(const LAS f32x4*)(tab + k * 128 + cl + 4);
;                 a8[0] += w0[0] * pg8::bf_lo(xq.x); a8[1] += w0[1] * pg8::bf_hi(xq.x); a8[2] += w0[2] * pg8::bf_lo(xq.y); a8[3] += w0[3] * pg8::bf_hi(xq.y);
;                 a8[4] += w1[0] * pg8::bf_lo(xq.z); a8[5] += w1[1] * pg8::bf_hi(xq.z); a8[6] += w1[2] * pg8::bf_lo(xq.w); a8[7] += w1[3] * pg8::bf_hi(xq.w); }
;             v4u u4; u4.x = pg8::cvt_pk_bf16(a8[0], a8[1]); u4.y = pg8::cvt_pk_bf16(a8[2], a8[3]); u4.z = pg8::cvt_pk_bf16(a8[4], a8[5]); u4.w = pg8::cvt_pk_bf16(a8[6], a8[7]); bfr[ks] = __builtin_bit_cast(bf16x8, u4);
	v_cndmask_b32_e32 v196, 0, v196, vcc
	v_cndmask_b32_e32 v197, 0, v197, vcc
	v_cndmask_b32_e32 v198, 0, v198, vcc
	v_cndmask_b32_e32 v199, 0, v199, vcc
	v_lshlrev_b32_e32 v248, 16, v196
	v_lshlrev_b32_e32 v249, 16, v197
	v_lshlrev_b32_e32 v250, 16, v198
	v_lshlrev_b32_e32 v251, 16, v199
	v_and_b32_e32 v196, 0xffff0000, v196
	v_and_b32_e32 v197, 0xffff0000, v197
	v_and_b32_e32 v198, 0xffff0000, v198
	v_and_b32_e32 v199, 0xffff0000, v199
	v_fma_f32 v144, v204, v248, v188
	v_fma_f32 v145, v205, v196, v189
	v_fma_f32 v146, v206, v249, v190
	v_fma_f32 v147, v207, v197, v191
	v_fma_f32 v148, v208, v250, v192
	v_fma_f32 v149, v209, v198, v193
	v_fma_f32 v150, v210, v251, v194
	v_fma_f32 v143, v211, v199, v195
	v_cndmask_b32_e64 v200, 0, v200, s[46:47]
	v_cndmask_b32_e64 v201, 0, v201, s[46:47]
	v_cndmask_b32_e64 v202, 0, v202, s[46:47]
	v_cndmask_b32_e64 v203, 0, v203, s[46:47]
	v_lshlrev_b32_e32 v248, 16, v200
	v_lshlrev_b32_e32 v249, 16, v201
	v_lshlrev_b32_e32 v250, 16, v202
	v_lshlrev_b32_e32 v251, 16, v203
	v_and_b32_e32 v200, 0xffff0000, v200
	v_and_b32_e32 v201, 0xffff0000, v201
	v_and_b32_e32 v202, 0xffff0000, v202
	v_and_b32_e32 v203, 0xffff0000, v203
	v_fmac_f32_e32 v144, v212, v248
	v_fmac_f32_e32 v145, v213, v200
	v_fmac_f32_e32 v146, v214, v249
	v_fmac_f32_e32 v147, v215, v201
	v_fmac_f32_e32 v148, v216, v250
	v_fmac_f32_e32 v149, v217, v202
	v_fmac_f32_e32 v150, v218, v251
	v_fmac_f32_e32 v143, v219, v203
	v_add_u32_e32 v250, v28, v124
	v_add_u32_e32 v251, v28, v125
	ds_read_b128 v[188:191], v115 offset:2304
	ds_read_b128 v[192:195], v115 offset:2320
	ds_read_b128 v[196:199], v250 offset:45056
	ds_read_b128 v[200:203], v251 offset:45312
	ds_read_b128 v[204:207], v115 offset:256
	ds_read_b128 v[208:211], v115 offset:272
	ds_read_b128 v[212:215], v115 offset:768
	ds_read_b128 v[216:219], v115 offset:784
	s_waitcnt lgkmcnt(8)
	v_cndmask_b32_e64 v220, v220, 0, s[44:45]
	v_cndmask_b32_e64 v221, v221, 0, s[44:45]
	v_cndmask_b32_e64 v222, v222, 0, s[44:45]
	v_cndmask_b32_e64 v223, v223, 0, s[44:45]
	v_lshlrev_b32_e32 v248, 16, v220
	v_lshlrev_b32_e32 v249, 16, v221
	v_lshlrev_b32_e32 v250, 16, v222
	v_lshlrev_b32_e32 v251, 16, v223
	v_and_b32_e32 v220, 0xffff0000, v220
	v_and_b32_e32 v221, 0xffff0000, v221
	v_and_b32_e32 v222, 0xffff0000, v222
	v_and_b32_e32 v223, 0xffff0000, v223
	v_mul_f32_e32 v228, v228, v248
	v_mul_f32_e32 v229, v229, v220
	v_mul_f32_e32 v230, v230, v249
	v_mul_f32_e32 v231, v231, v221
	v_mul_f32_e32 v236, v236, v250
	v_mul_f32_e32 v237, v237, v222
	v_mul_f32_e32 v238, v238, v251
	v_mul_f32_e32 v239, v239, v223
	v_lshlrev_b32_e32 v248, 16, v224
	v_lshlrev_b32_e32 v249, 16, v225
	v_lshlrev_b32_e32 v250, 16, v226
	v_lshlrev_b32_e32 v251, 16, v227
	v_and_b32_e32 v224, 0xffff0000, v224
	v_and_b32_e32 v225, 0xffff0000, v225
	v_and_b32_e32 v226, 0xffff0000, v226
	v_and_b32_e32 v227, 0xffff0000, v227
	v_mul_f32_e32 v240, v240, v248
	v_mul_f32_e32 v241, v241, v224
	v_mul_f32_e32 v242, v242, v249
	v_mul_f32_e32 v243, v243, v225
	v_mul_f32_e32 v244, v244, v250
	v_mul_f32_e32 v245, v245, v226
	v_mul_f32_e32 v246, v246, v251
	v_mul_f32_e32 v247, v247, v227
	v_add_f32_e32 v144, v144, v228
	v_add_f32_e32 v145, v145, v229
	v_add_f32_e32 v146, v146, v230
	v_add_f32_e32 v147, v147, v231
	v_add_f32_e32 v148, v148, v236
	v_add_f32_e32 v149, v149, v237
	v_add_f32_e32 v150, v150, v238
	v_add_f32_e32 v143, v143, v239
	v_add_f32_e32 v144, v144, v240
	v_add_f32_e32 v145, v145, v241
	v_add_f32_e32 v146, v146, v242
	v_add_f32_e32 v147, v147, v243
	v_add_f32_e32 v148, v148, v244
	v_add_f32_e32 v149, v149, v245
	v_add_f32_e32 v150, v150, v246
	v_add_f32_e32 v143, v143, v247
	v_add_u32_e32 v250, v28, v126
	v_add_u32_e32 v251, v28, v127
	ds_read_b128 v[220:223], v250 offset:45568
	ds_read_b128 v[224:227], v251 offset:45824
	ds_read_b128 v[228:231], v115 offset:1280
	ds_read_b128 v[236:239], v115 offset:1296
	ds_read_b128 v[240:243], v115 offset:1792
	ds_read_b128 v[244:247], v115 offset:1808
	v_cvt_pk_bf16_f32 v16, v144, v145
	v_cvt_pk_bf16_f32 v17, v146, v147
	v_cvt_pk_bf16_f32 v18, v148, v149
	v_cvt_pk_bf16_f32 v19, v150, v143
	s_waitcnt lgkmcnt(6)
	v_cndmask_b32_e32 v196, 0, v196, vcc
	v_cndmask_b32_e32 v197, 0, v197, vcc
	v_cndmask_b32_e32 v198, 0, v198, vcc
	v_cndmask_b32_e32 v199, 0, v199, vcc
	v_lshlrev_b32_e32 v248, 16, v196
	v_lshlrev_b32_e32 v249, 16, v197
	v_lshlrev_b32_e32 v250, 16, v198
	v_lshlrev_b32_e32 v251, 16, v199
	v_and_b32_e32 v196, 0xffff0000, v196
	v_and_b32_e32 v197, 0xffff0000, v197
	v_and_b32_e32 v198, 0xffff0000, v198
	v_and_b32_e32 v199, 0xffff0000, v199
	v_fma_f32 v151, v204, v248, v188
	v_fma_f32 v152, v205, v196, v189
	v_fma_f32 v153, v206, v249, v190
	v_fma_f32 v154, v207, v197, v191
	v_fma_f32 v155, v208, v250, v192
	v_fma_f32 v158, v209, v198, v193
	v_fma_f32 v159, v210, v251, v194
	v_fma_f32 v160, v211, v199, v195
	v_cndmask_b32_e64 v200, 0, v200, s[46:47]
	v_cndmask_b32_e64 v201, 0, v201, s[46:47]
	v_cndmask_b32_e64 v202, 0, v202, s[46:47]
	v_cndmask_b32_e64 v203, 0, v203, s[46:47]
	v_lshlrev_b32_e32 v248, 16, v200
	v_lshlrev_b32_e32 v249, 16, v201
	v_lshlrev_b32_e32 v250, 16, v202
	v_lshlrev_b32_e32 v251, 16, v203
	v_and_b32_e32 v200, 0xffff0000, v200
	v_and_b32_e32 v201, 0xffff0000, v201
	v_and_b32_e32 v202, 0xffff0000, v202
	v_and_b32_e32 v203, 0xffff0000, v203
	v_fmac_f32_e32 v151, v212, v248
	v_fmac_f32_e32 v152, v213, v200
	v_fmac_f32_e32 v153, v214, v249
	v_fmac_f32_e32 v154, v215, v201
	v_fmac_f32_e32 v155, v216, v250
	v_fmac_f32_e32 v158, v217, v202
	v_fmac_f32_e32 v159, v218, v251
	v_fmac_f32_e32 v160, v219, v203
	v_add_u32_e32 v250, v28, v128
	v_add_u32_e32 v251, v28, v129
	ds_read_b128 v[188:191], v115 offset:2432
	ds_read_b128 v[192:195], v115 offset:2448
	ds_read_b128 v[196:199], v250 offset:45056
	ds_read_b128 v[200:203], v251 offset:45312
	ds_read_b128 v[204:207], v115 offset:384
	ds_read_b128 v[208:211], v115 offset:400
	ds_read_b128 v[212:215], v115 offset:896
	ds_read_b128 v[216:219], v115 offset:912
	s_waitcnt lgkmcnt(8)
; __device__ __forceinline__ unsigned cvt_pk_bf16(float lo, float hi) { unsigned r; asm volatile("v_cvt_pk_bf16_f32 %0, %1, %2" : "=v"(r) : "v"(lo), "v"(hi)); return r; }
; __device__ __forceinline__ float bf_lo(unsigned w) { return __uint_as_float(w << 16); }
; #define LAS __attribute__((address_space(3)))
; __device__ __forceinline__ void lru_item(const Frame& F, const bf16* XR, bf16* XGYL, const float* conv_w, const float* conv_b, const float* wa, const float* ba, const float* wx, const float* bx, const float* lam, int b, int hh, int j2) {
;     ...
;         for (int ks = 0; ks < 4; ++ks) { const int cl = 32 * ks + 8 * g; float a8[8];
;             { const f32x4 b0 = *(const LAS f32x4*)(tab + 512 + cl), b1 = *(const LAS f32x4*)(tab + 512 + cl + 4); a8[0] = b0[0]; a8[1] = b0[1]; a8[2] = b0[2]; a8[3] = b0[3]; a8[4] = b1[0]; a8[5] = b1[1]; a8[6] = b1[2]; a8[7] = b1[3]; }
; #pragma unroll
;             for (int k = 0; k < 4; ++k) { const int rr = 16 * w + tl + k; v4u xq = *(const LAS v4u*)(xb + k * 256 + (((4 * ks + g) ^ (rr & 15)) << 4));
;                 const bool inb = (chunk > 0) || (rr >= 3); xq.x = inb ? xq.x : 0u; xq.y = inb ? xq.y : 0u; xq.z = inb ? xq.z : 0u; xq.w = inb ? xq.w : 0u;
;                 const f32x4 w0 = *(const LAS f32x4*)(tab + k * 128 + cl), w1 = *(const LAS f32x4*)(tab + k * 128 + cl + 4);
;                 a8[0] += w0[0] * pg8::bf_lo(xq.x); a8[1] += w0[1] * pg8::bf_hi(xq.x); a8[2] += w0[2] * pg8::bf_lo(xq.y); a8[3] += w0[3] * pg8::bf_hi(xq.y);
;                 a8[4] += w1[0] * pg8::bf_lo(xq.z); a8[5] += w1[1] * pg8::bf_hi(xq.z); a8[6] += w1[2] * pg8::bf_lo(xq.w); a8[7] += w1[3] * pg8::bf_hi(xq.w); }
;             v4u u4; u4.x = pg8::cvt_pk_bf16(a8[0], a8[1]); u4.y = pg8::cvt_pk_bf16(a8[2], a8[3]); u4.z = pg8::cvt_pk_bf16(a8[4], a8[5]); u4.w = pg8::cvt_pk_bf16(a8[6], a8[7]); bfr[ks] = __builtin_bit_cast(bf16x8, u4);
; #pragma unroll
;             for (int i = 0; i < 8; ++i) { xcf[i] = (ks == 2 * j2) ? a8[i] : xcf[i]; xcf[8 + i] = (ks == 2 * j2 + 1) ? a8[i] : xcf[8 + i]; } }
;         f32x4 pa[8];
; #pragma unroll
;         for (int T = 0; T < 8; ++T) { pa[T] = (f32x4){0.f, 0.f, 0.f, 0.f};
; #pragma unroll
;             for (int ks = 0; ks < 4; ++ks) { const bf16x8 wfr = *(const LAS bf16x8*)(wfl + ((T * 4 + ks) * 64 + lane) * 16); pa[T] = __builtin_amdgcn_mfma_f32_16x16x32_bf16(wfr, bfr[ks], pa[T], 0, 0, 0); } }
	v_cndmask_b32_e64 v220, v220, 0, s[44:45]
	v_cndmask_b32_e64 v221, v221, 0, s[44:45]
	v_cndmask_b32_e64 v222, v222, 0, s[44:45]
	v_cndmask_b32_e64 v223, v223, 0, s[44:45]
	v_lshlrev_b32_e32 v248, 16, v220
	v_lshlrev_b32_e32 v249, 16, v221
	v_lshlrev_b32_e32 v250, 16, v222
	v_lshlrev_b32_e32 v251, 16, v223
	v_and_b32_e32 v220, 0xffff0000, v220
	v_and_b32_e32 v221, 0xffff0000, v221
	v_and_b32_e32 v222, 0xffff0000, v222
	v_and_b32_e32 v223, 0xffff0000, v223
	v_mul_f32_e32 v228, v228, v248
	v_mul_f32_e32 v229, v229, v220
	v_mul_f32_e32 v230, v230, v249
	v_mul_f32_e32 v231, v231, v221
	v_mul_f32_e32 v236, v236, v250
	v_mul_f32_e32 v237, v237, v222
	v_mul_f32_e32 v238, v238, v251
	v_mul_f32_e32 v239, v239, v223
	v_lshlrev_b32_e32 v248, 16, v224
	v_lshlrev_b32_e32 v249, 16, v225
	v_lshlrev_b32_e32 v250, 16, v226
	v_lshlrev_b32_e32 v251, 16, v227
	v_and_b32_e32 v224, 0xffff0000, v224
	v_and_b32_e32 v225, 0xffff0000, v225
	v_and_b32_e32 v226, 0xffff0000, v226
	v_and_b32_e32 v227, 0xffff0000, v227
	v_mul_f32_e32 v240, v240, v248
	v_mul_f32_e32 v241, v241, v224
	v_mul_f32_e32 v242, v242, v249
	v_mul_f32_e32 v243, v243, v225
	v_mul_f32_e32 v244, v244, v250
	v_mul_f32_e32 v245, v245, v226
	v_mul_f32_e32 v246, v246, v251
	v_mul_f32_e32 v247, v247, v227
	v_add_f32_e32 v151, v151, v228
	v_add_f32_e32 v152, v152, v229
	v_add_f32_e32 v153, v153, v230
	v_add_f32_e32 v154, v154, v231
	v_add_f32_e32 v155, v155, v236
	v_add_f32_e32 v158, v158, v237
	v_add_f32_e32 v159, v159, v238
	v_add_f32_e32 v160, v160, v239
	v_add_f32_e32 v151, v151, v240
	v_add_f32_e32 v152, v152, v241
	v_add_f32_e32 v153, v153, v242
	v_add_f32_e32 v154, v154, v243
	v_add_f32_e32 v155, v155, v244
	v_add_f32_e32 v158, v158, v245
	v_add_f32_e32 v159, v159, v246
	v_add_f32_e32 v160, v160, v247
	v_add_u32_e32 v250, v28, v130
	v_add_u32_e32 v251, v28, v131
	ds_read_b128 v[220:223], v250 offset:45568
	ds_read_b128 v[224:227], v251 offset:45824
	ds_read_b128 v[228:231], v115 offset:1408
	ds_read_b128 v[236:239], v115 offset:1424
	ds_read_b128 v[240:243], v115 offset:1920
	ds_read_b128 v[244:247], v115 offset:1936
	v_cvt_pk_bf16_f32 v36, v151, v152
	v_cvt_pk_bf16_f32 v37, v153, v154
	v_cvt_pk_bf16_f32 v38, v155, v158
	v_cvt_pk_bf16_f32 v39, v159, v160
	s_waitcnt lgkmcnt(6)
	v_cndmask_b32_e32 v196, 0, v196, vcc
	v_cndmask_b32_e32 v197, 0, v197, vcc
	v_cndmask_b32_e32 v198, 0, v198, vcc
	v_cndmask_b32_e32 v199, 0, v199, vcc
	v_lshlrev_b32_e32 v248, 16, v196
	v_lshlrev_b32_e32 v249, 16, v197
	v_lshlrev_b32_e32 v250, 16, v198
	v_lshlrev_b32_e32 v251, 16, v199
	v_and_b32_e32 v196, 0xffff0000, v196
	v_and_b32_e32 v197, 0xffff0000, v197
	v_and_b32_e32 v198, 0xffff0000, v198
	v_and_b32_e32 v199, 0xffff0000, v199
	v_fma_f32 v162, v204, v248, v188
	v_fma_f32 v163, v205, v196, v189
	v_fma_f32 v164, v206, v249, v190
	v_fma_f32 v165, v207, v197, v191
	v_fma_f32 v166, v208, v250, v192
	v_fma_f32 v167, v209, v198, v193
	v_fma_f32 v168, v210, v251, v194
	v_fma_f32 v161, v211, v199, v195
	v_cndmask_b32_e64 v200, 0, v200, s[46:47]
	v_cndmask_b32_e64 v201, 0, v201, s[46:47]
	v_cndmask_b32_e64 v202, 0, v202, s[46:47]
	v_cndmask_b32_e64 v203, 0, v203, s[46:47]
	v_lshlrev_b32_e32 v248, 16, v200
	v_lshlrev_b32_e32 v249, 16, v201
	v_lshlrev_b32_e32 v250, 16, v202
	v_lshlrev_b32_e32 v251, 16, v203
	v_and_b32_e32 v200, 0xffff0000, v200
	v_and_b32_e32 v201, 0xffff0000, v201
	v_and_b32_e32 v202, 0xffff0000, v202
	v_and_b32_e32 v203, 0xffff0000, v203
	v_fmac_f32_e32 v162, v212, v248
	v_fmac_f32_e32 v163, v213, v200
	v_fmac_f32_e32 v164, v214, v249
	v_fmac_f32_e32 v165, v215, v201
	v_fmac_f32_e32 v166, v216, v250
	v_fmac_f32_e32 v167, v217, v202
	v_fmac_f32_e32 v168, v218, v251
	v_fmac_f32_e32 v161, v219, v203
	s_waitcnt lgkmcnt(0)
	v_cndmask_b32_e64 v220, v220, 0, s[44:45]
	v_cndmask_b32_e64 v221, v221, 0, s[44:45]
	v_cndmask_b32_e64 v222, v222, 0, s[44:45]
	v_cndmask_b32_e64 v223, v223, 0, s[44:45]
	v_lshlrev_b32_e32 v248, 16, v220
	v_lshlrev_b32_e32 v249, 16, v221
	v_lshlrev_b32_e32 v250, 16, v222
	v_lshlrev_b32_e32 v251, 16, v223
	v_and_b32_e32 v220, 0xffff0000, v220
	v_and_b32_e32 v221, 0xffff0000, v221
	v_and_b32_e32 v222, 0xffff0000, v222
	v_and_b32_e32 v223, 0xffff0000, v223
	v_mul_f32_e32 v228, v228, v248
	v_mul_f32_e32 v229, v229, v220
	v_mul_f32_e32 v230, v230, v249
	v_mul_f32_e32 v231, v231, v221
	v_mul_f32_e32 v236, v236, v250
	v_mul_f32_e32 v237, v237, v222
	v_mul_f32_e32 v238, v238, v251
	v_mul_f32_e32 v239, v239, v223
	v_lshlrev_b32_e32 v248, 16, v224
	v_lshlrev_b32_e32 v249, 16, v225
	v_lshlrev_b32_e32 v250, 16, v226
	v_lshlrev_b32_e32 v251, 16, v227
	v_and_b32_e32 v224, 0xffff0000, v224
	v_and_b32_e32 v225, 0xffff0000, v225
	v_and_b32_e32 v226, 0xffff0000, v226
	v_and_b32_e32 v227, 0xffff0000, v227
	v_mul_f32_e32 v240, v240, v248
	v_mul_f32_e32 v241, v241, v224
	v_mul_f32_e32 v242, v242, v249
	v_mul_f32_e32 v243, v243, v225
	v_mul_f32_e32 v244, v244, v250
	v_mul_f32_e32 v245, v245, v226
	v_mul_f32_e32 v246, v246, v251
	v_mul_f32_e32 v247, v247, v227
	v_add_f32_e32 v162, v162, v228
	v_add_f32_e32 v163, v163, v229
	v_add_f32_e32 v164, v164, v230
	v_add_f32_e32 v165, v165, v231
	v_add_f32_e32 v166, v166, v236
	v_add_f32_e32 v167, v167, v237
	v_add_f32_e32 v168, v168, v238
	v_add_f32_e32 v161, v161, v239
	v_add_f32_e32 v162, v162, v240
	v_add_f32_e32 v163, v163, v241
	v_add_f32_e32 v164, v164, v242
	v_add_f32_e32 v165, v165, v243
	v_add_f32_e32 v166, v166, v244
	v_add_f32_e32 v167, v167, v245
	v_add_f32_e32 v168, v168, v246
	v_add_f32_e32 v161, v161, v247
	v_cvt_pk_bf16_f32 v52, v162, v163
	v_cvt_pk_bf16_f32 v53, v164, v165
	v_cvt_pk_bf16_f32 v54, v166, v167
	v_cvt_pk_bf16_f32 v55, v168, v161
	v_add_u32_e32 v60, 0, v108
	ds_read_b128 v[188:191], v60 offset:12288
	ds_read_b128 v[192:195], v60 offset:13312
	ds_read_b128 v[196:199], v60 offset:14336
	ds_read_b128 v[200:203], v60 offset:15360
	ds_read_b128 v[204:207], v60 offset:16384
	ds_read_b128 v[208:211], v60 offset:17408
	ds_read_b128 v[212:215], v60 offset:18432
	ds_read_b128 v[216:219], v60 offset:19456
	s_waitcnt lgkmcnt(7)
; __device__ __forceinline__ float fsigmoid(float x) { return __builtin_amdgcn_rcpf(1.0f + __builtin_amdgcn_exp2f(-1.4426950408889634f * x)); }
; #define LAS __attribute__((address_space(3)))
; __device__ __forceinline__ void lru_item(const Frame& F, const bf16* XR, bf16* XGYL, const float* conv_w, const float* conv_b, const float* wa, const float* ba, const float* wx, const float* bx, const float* lam, int b, int hh, int j2) {
;     ...
;         for (int T = 0; T < 8; ++T) { pa[T] = (f32x4){0.f, 0.f, 0.f, 0.f};
; #pragma unroll
;             for (int ks = 0; ks < 4; ++ks) { const bf16x8 wfr = *(const LAS bf16x8*)(wfl + ((T * 4 + ks) * 64 + lane) * 16); pa[T] = __builtin_amdgcn_mfma_f32_16x16x32_bf16(wfr, bfr[ks], pa[T], 0, 0, 0); } }
;         float av[16], uv[16];
; #pragma unroll
;         for (int s2 = 0; s2 < 2; ++s2) {
;             const f32x4 ba0 = *(const LAS f32x4*)(ctab + 32 * s2 + 8 * g), ba1 = *(const LAS f32x4*)(ctab + 32 * s2 + 8 * g + 4);
;             const f32x4 bx0 = *(const LAS f32x4*)(ctab + 64 + 32 * s2 + 8 * g), bx1 = *(const LAS f32x4*)(ctab + 64 + 32 * s2 + 8 * g + 4);
;             const f32x4 sp0 = *(const LAS f32x4*)(ctab + 128 + 32 * s2 + 8 * g), sp1 = *(const LAS f32x4*)(ctab + 128 + 32 * s2 + 8 * g + 4);
; #pragma unroll
;             for (int i = 0; i < 8; ++i) { const float bai = (i < 4) ? ba0[i & 3] : ba1[i & 3], bxi = (i < 4) ? bx0[i & 3] : bx1[i & 3], spi = (i < 4) ? sp0[i & 3] : sp1[i & 3];
;                 const float rp = pa[s2 * 2 + (i >> 2)][i & 3] + bai, xp = pa[4 + s2 * 2 + (i >> 2)][i & 3] + bxi;
;                 const float rr = pg8::fsigmoid(rp), ig = pg8::fsigmoid(xp), la = -spi * rr, x2 = 2.0f * la;
;                 const float a = __builtin_amdgcn_exp2f(LOG2E * la);
	v_mfma_f32_16x16x32_bf16 v[48:51], v[188:191], v[12:15], 0
	ds_read_b128 v[188:191], v60 offset:20480
	s_waitcnt lgkmcnt(7)
	v_mfma_f32_16x16x32_bf16 v[48:51], v[192:195], v[16:19], v[48:51]
	ds_read_b128 v[192:195], v60 offset:21504
	s_waitcnt lgkmcnt(7)
	v_mfma_f32_16x16x32_bf16 v[48:51], v[196:199], v[36:39], v[48:51]
	ds_read_b128 v[196:199], v60 offset:22528
	s_waitcnt lgkmcnt(7)
	v_mfma_f32_16x16x32_bf16 v[48:51], v[200:203], v[52:55], v[48:51]
	ds_read_b128 v[200:203], v60 offset:23552
	s_waitcnt lgkmcnt(7)
	v_mfma_f32_16x16x32_bf16 v[44:47], v[204:207], v[12:15], 0
	ds_read_b128 v[204:207], v60 offset:24576
	s_waitcnt lgkmcnt(7)
	v_mfma_f32_16x16x32_bf16 v[44:47], v[208:211], v[16:19], v[44:47]
	ds_read_b128 v[208:211], v60 offset:25600
	s_waitcnt lgkmcnt(7)
	v_mfma_f32_16x16x32_bf16 v[44:47], v[212:215], v[36:39], v[44:47]
	ds_read_b128 v[212:215], v60 offset:26624
	s_waitcnt lgkmcnt(7)
	v_mfma_f32_16x16x32_bf16 v[44:47], v[216:219], v[52:55], v[44:47]
	ds_read_b128 v[216:219], v60 offset:27648
	s_waitcnt lgkmcnt(7)
	v_mfma_f32_16x16x32_bf16 v[40:43], v[188:191], v[12:15], 0
	ds_read_b128 v[188:191], v60 offset:28672
	s_waitcnt lgkmcnt(7)
	v_mfma_f32_16x16x32_bf16 v[40:43], v[192:195], v[16:19], v[40:43]
	ds_read_b128 v[192:195], v60 offset:29696
	s_waitcnt lgkmcnt(7)
	v_mfma_f32_16x16x32_bf16 v[40:43], v[196:199], v[36:39], v[40:43]
	ds_read_b128 v[196:199], v60 offset:30720
	s_waitcnt lgkmcnt(7)
	v_mfma_f32_16x16x32_bf16 v[40:43], v[200:203], v[52:55], v[40:43]
	ds_read_b128 v[200:203], v60 offset:31744
	s_waitcnt lgkmcnt(7)
	v_mfma_f32_16x16x32_bf16 v[28:31], v[204:207], v[12:15], 0
	ds_read_b128 v[204:207], v60 offset:32768
	s_waitcnt lgkmcnt(7)
	v_mfma_f32_16x16x32_bf16 v[28:31], v[208:211], v[16:19], v[28:31]
	ds_read_b128 v[208:211], v60 offset:33792
	s_waitcnt lgkmcnt(7)
	v_mfma_f32_16x16x32_bf16 v[28:31], v[212:215], v[36:39], v[28:31]
	ds_read_b128 v[212:215], v60 offset:34816
	s_waitcnt lgkmcnt(7)
	v_mfma_f32_16x16x32_bf16 v[28:31], v[216:219], v[52:55], v[28:31]
	ds_read_b128 v[216:219], v60 offset:35840
	s_waitcnt lgkmcnt(7)
	v_mfma_f32_16x16x32_bf16 v[20:23], v[188:191], v[12:15], 0
	ds_read_b128 v[188:191], v60 offset:36864
	s_waitcnt lgkmcnt(7)
	v_mfma_f32_16x16x32_bf16 v[20:23], v[192:195], v[16:19], v[20:23]
	ds_read_b128 v[192:195], v60 offset:37888
	s_waitcnt lgkmcnt(7)
	v_mfma_f32_16x16x32_bf16 v[20:23], v[196:199], v[36:39], v[20:23]
	ds_read_b128 v[196:199], v60 offset:38912
	s_waitcnt lgkmcnt(7)
	v_mfma_f32_16x16x32_bf16 v[20:23], v[200:203], v[52:55], v[20:23]
	ds_read_b128 v[200:203], v60 offset:39936
	s_waitcnt lgkmcnt(7)
	v_mfma_f32_16x16x32_bf16 v[24:27], v[204:207], v[12:15], 0
	ds_read_b128 v[204:207], v60 offset:40960
	s_waitcnt lgkmcnt(7)
	v_mfma_f32_16x16x32_bf16 v[24:27], v[208:211], v[16:19], v[24:27]
	ds_read_b128 v[208:211], v60 offset:41984
	s_waitcnt lgkmcnt(7)
	v_mfma_f32_16x16x32_bf16 v[24:27], v[212:215], v[36:39], v[24:27]
	ds_read_b128 v[212:215], v60 offset:43008
	s_waitcnt lgkmcnt(7)
	v_mfma_f32_16x16x32_bf16 v[24:27], v[216:219], v[52:55], v[24:27]
	ds_read_b128 v[216:219], v60 offset:44032
	s_waitcnt lgkmcnt(7)
	v_mfma_f32_16x16x32_bf16 v[32:35], v[188:191], v[12:15], 0
	s_waitcnt lgkmcnt(6)
	v_mfma_f32_16x16x32_bf16 v[32:35], v[192:195], v[16:19], v[32:35]
	s_waitcnt lgkmcnt(5)
	v_mfma_f32_16x16x32_bf16 v[32:35], v[196:199], v[36:39], v[32:35]
	s_waitcnt lgkmcnt(4)
	v_mfma_f32_16x16x32_bf16 v[32:35], v[200:203], v[52:55], v[32:35]
	s_waitcnt lgkmcnt(3)
	v_mfma_f32_16x16x32_bf16 v[220:223], v[204:207], v[12:15], 0
	s_waitcnt lgkmcnt(2)
	v_mfma_f32_16x16x32_bf16 v[220:223], v[208:211], v[16:19], v[220:223]
	s_waitcnt lgkmcnt(1)
	v_mfma_f32_16x16x32_bf16 v[220:223], v[212:215], v[36:39], v[220:223]
	s_waitcnt lgkmcnt(0)
	v_mfma_f32_16x16x32_bf16 v[16:19], v[216:219], v[52:55], v[220:223]
	ds_read_b128 v[60:63], v115 offset:2560
	ds_read_b128 v[56:59], v115 offset:2576
	s_nop 2
	ds_read_b128 v[12:15], v115 offset:2816
	ds_read_b128 v[36:39], v115 offset:2832
	ds_read_b128 v[64:67], v115 offset:3072
	ds_read_b128 v[52:55], v115 offset:3088
	s_waitcnt lgkmcnt(0)
	v_add_f32_e32 v48, v48, v60
	v_mul_f32_e32 v48, 0xbfb8aa3b, v48
	v_exp_f32_e32 v48, v48
	s_nop 0
	v_add_f32_e32 v48, 1.0, v48
	v_rcp_f32_e32 v48, v48
	s_nop 0
	v_mul_f32_e64 v60, v48, -v64
	v_add_f32_e32 v48, v60, v60
	v_mul_f32_e32 v60, 0x3fb8aa3b, v60
	v_exp_f32_e32 v169, v60
	v_cmp_nlt_f32_e32 vcc, s92, v48
	s_and_saveexec_b64 s[2:3], vcc
	s_xor_b64 s[2:3], exec, s[2:3]
	v_fma_f32 v171, v169, v169, -1.0
	s_andn2_saveexec_b64 s[2:3], s[2:3]
	v_fmamk_f32 v60, v48, 0x3c088888, v136
	v_fmaak_f32 v60, v48, v60, 0x3e2aaaab
	v_fma_f32 v60, v48, v60, 0.5
	v_fma_f32 v60, v48, v60, 1.0
	v_mul_f32_e32 v171, v48, v60
	s_or_b64 exec, exec, s[2:3]
	v_add_f32_e32 v48, v49, v61
	v_mul_f32_e32 v48, 0xbfb8aa3b, v48
	v_exp_f32_e32 v48, v48
	s_nop 0
	v_add_f32_e32 v48, 1.0, v48
	v_rcp_f32_e32 v48, v48
	s_nop 0
	v_mul_f32_e64 v48, v48, -v65
	v_mul_f32_e32 v49, 0x3fb8aa3b, v48
	v_exp_f32_e32 v170, v49
	v_add_f32_e32 v48, v48, v48
	v_cmp_nlt_f32_e32 vcc, s92, v48
	s_and_saveexec_b64 s[2:3], vcc
	s_xor_b64 s[2:3], exec, s[2:3]
	v_fma_f32 v176, v170, v170, -1.0
	s_andn2_saveexec_b64 s[2:3], s[2:3]
	v_fmamk_f32 v49, v48, 0x3c088888, v136
	v_fmaak_f32 v49, v48, v49, 0x3e2aaaab
	v_fma_f32 v49, v48, v49, 0.5
	v_fma_f32 v49, v48, v49, 1.0
	v_mul_f32_e32 v176, v48, v49
	s_or_b64 exec, exec, s[2:3]
	v_add_f32_e32 v48, v50, v62
	v_mul_f32_e32 v48, 0xbfb8aa3b, v48
	v_exp_f32_e32 v48, v48
	s_nop 0
	v_add_f32_e32 v48, 1.0, v48
	v_rcp_f32_e32 v48, v48
	s_nop 0
	v_mul_f32_e64 v48, v48, -v66
	v_mul_f32_e32 v49, 0x3fb8aa3b, v48
	v_exp_f32_e32 v172, v49
; __device__ __forceinline__ float fsigmoid(float x) { return __builtin_amdgcn_rcpf(1.0f + __builtin_amdgcn_exp2f(-1.4426950408889634f * x)); }
; #define LAS __attribute__((address_space(3)))
; __device__ __forceinline__ void lru_item(const Frame& F, const bf16* XR, bf16* XGYL, const float* conv_w, const float* conv_b, const float* wa, const float* ba, const float* wx, const float* bx, const float* lam, int b, int hh, int j2) {
;     ...
;             const f32x4 ba0 = *(const LAS f32x4*)(ctab + 32 * s2 + 8 * g), ba1 = *(const LAS f32x4*)(ctab + 32 * s2 + 8 * g + 4);
;             const f32x4 bx0 = *(const LAS f32x4*)(ctab + 64 + 32 * s2 + 8 * g), bx1 = *(const LAS f32x4*)(ctab + 64 + 32 * s2 + 8 * g + 4);
;             const f32x4 sp0 = *(const LAS f32x4*)(ctab + 128 + 32 * s2 + 8 * g), sp1 = *(const LAS f32x4*)(ctab + 128 + 32 * s2 + 8 * g + 4);
; #pragma unroll
;             for (int i = 0; i < 8; ++i) { const float bai = (i < 4) ? ba0[i & 3] : ba1[i & 3], bxi = (i < 4) ? bx0[i & 3] : bx1[i & 3], spi = (i < 4) ? sp0[i & 3] : sp1[i & 3];
;                 const float rp = pa[s2 * 2 + (i >> 2)][i & 3] + bai, xp = pa[4 + s2 * 2 + (i >> 2)][i & 3] + bxi;
;                 const float rr = pg8::fsigmoid(rp), ig = pg8::fsigmoid(xp), la = -spi * rr, x2 = 2.0f * la;
;                 const float a = __builtin_amdgcn_exp2f(LOG2E * la);
;                 const float em1 = (x2 > -0.3f) ? x2 * (1.0f + x2 * (0.5f + x2 * (0.16666667f + x2 * (0.041666668f + x2 * 0.0083333333f)))) : (a * a - 1.0f);
;                 av[8 * s2 + i] = a; uv[8 * s2 + i] = __builtin_amdgcn_sqrtf(-em1) * ig * xcf[8 * s2 + i]; } }
	v_add_f32_e32 v48, v48, v48
	v_cmp_nlt_f32_e32 vcc, s92, v48
	s_and_saveexec_b64 s[2:3], vcc
	s_xor_b64 s[2:3], exec, s[2:3]
	v_fma_f32 v179, v172, v172, -1.0
	s_andn2_saveexec_b64 s[2:3], s[2:3]
	v_fmamk_f32 v49, v48, 0x3c088888, v136
	v_fmaak_f32 v49, v48, v49, 0x3e2aaaab
	v_fma_f32 v49, v48, v49, 0.5
	v_fma_f32 v49, v48, v49, 1.0
	v_mul_f32_e32 v179, v48, v49
	s_or_b64 exec, exec, s[2:3]
	v_add_f32_e32 v48, v51, v63
	v_mul_f32_e32 v48, 0xbfb8aa3b, v48
	v_exp_f32_e32 v48, v48
	s_nop 0
	v_add_f32_e32 v48, 1.0, v48
	v_rcp_f32_e32 v48, v48
	s_nop 0
	v_mul_f32_e64 v48, v48, -v67
	v_mul_f32_e32 v49, 0x3fb8aa3b, v48
	v_exp_f32_e32 v173, v49
	v_add_f32_e32 v48, v48, v48
	v_cmp_nlt_f32_e32 vcc, s92, v48
	s_and_saveexec_b64 s[2:3], vcc
	s_xor_b64 s[2:3], exec, s[2:3]
	v_fma_f32 v180, v173, v173, -1.0
	s_andn2_saveexec_b64 s[2:3], s[2:3]
	v_fmamk_f32 v49, v48, 0x3c088888, v136
	v_fmaak_f32 v49, v48, v49, 0x3e2aaaab
	v_fma_f32 v49, v48, v49, 0.5
	v_fma_f32 v49, v48, v49, 1.0
	v_mul_f32_e32 v180, v48, v49
	s_or_b64 exec, exec, s[2:3]
	v_add_f32_e32 v44, v44, v56
	v_mul_f32_e32 v44, 0xbfb8aa3b, v44
	v_exp_f32_e32 v44, v44
	s_nop 0
	v_add_f32_e32 v44, 1.0, v44
	v_rcp_f32_e32 v44, v44
	s_nop 0
	v_mul_f32_e64 v44, v44, -v52
	v_mul_f32_e32 v48, 0x3fb8aa3b, v44
	v_exp_f32_e32 v174, v48
	v_add_f32_e32 v44, v44, v44
	v_cmp_nlt_f32_e32 vcc, s92, v44
	s_and_saveexec_b64 s[2:3], vcc
	s_xor_b64 s[2:3], exec, s[2:3]
	v_fma_f32 v181, v174, v174, -1.0
	s_andn2_saveexec_b64 s[2:3], s[2:3]
	v_fmamk_f32 v48, v44, 0x3c088888, v136
	v_fmaak_f32 v48, v44, v48, 0x3e2aaaab
	v_fma_f32 v48, v44, v48, 0.5
	v_fma_f32 v48, v44, v48, 1.0
	v_mul_f32_e32 v181, v44, v48
	s_or_b64 exec, exec, s[2:3]
	v_add_f32_e32 v44, v45, v57
	v_mul_f32_e32 v44, 0xbfb8aa3b, v44
	v_exp_f32_e32 v44, v44
	s_nop 0
	v_add_f32_e32 v44, 1.0, v44
	v_rcp_f32_e32 v44, v44
	s_nop 0
	v_mul_f32_e64 v44, v44, -v53
	v_mul_f32_e32 v45, 0x3fb8aa3b, v44
	v_exp_f32_e32 v175, v45
	v_add_f32_e32 v44, v44, v44
	v_cmp_nlt_f32_e32 vcc, s92, v44
	s_and_saveexec_b64 s[2:3], vcc
	s_xor_b64 s[2:3], exec, s[2:3]
	v_fma_f32 v182, v175, v175, -1.0
	s_andn2_saveexec_b64 s[2:3], s[2:3]
	v_fmamk_f32 v45, v44, 0x3c088888, v136
	v_fmaak_f32 v45, v44, v45, 0x3e2aaaab
	v_fma_f32 v45, v44, v45, 0.5
	v_fma_f32 v45, v44, v45, 1.0
	v_mul_f32_e32 v182, v44, v45
	s_or_b64 exec, exec, s[2:3]
	v_add_f32_e32 v44, v46, v58
	v_mul_f32_e32 v44, 0xbfb8aa3b, v44
	v_exp_f32_e32 v44, v44
	s_nop 0
	v_add_f32_e32 v44, 1.0, v44
	v_rcp_f32_e32 v44, v44
	s_nop 0
	v_mul_f32_e64 v44, v44, -v54
	v_mul_f32_e32 v45, 0x3fb8aa3b, v44
	v_exp_f32_e32 v177, v45
	v_add_f32_e32 v44, v44, v44
	v_cmp_nlt_f32_e32 vcc, s92, v44
	s_and_saveexec_b64 s[2:3], vcc
	s_xor_b64 s[2:3], exec, s[2:3]
	v_fma_f32 v183, v177, v177, -1.0
	s_andn2_saveexec_b64 s[2:3], s[2:3]
	v_fmamk_f32 v45, v44, 0x3c088888, v136
	v_fmaak_f32 v45, v44, v45, 0x3e2aaaab
	v_fma_f32 v45, v44, v45, 0.5
	v_fma_f32 v45, v44, v45, 1.0
	v_mul_f32_e32 v183, v44, v45
	s_or_b64 exec, exec, s[2:3]
	v_add_f32_e32 v44, v47, v59
	v_mul_f32_e32 v44, 0xbfb8aa3b, v44
	v_exp_f32_e32 v44, v44
	s_nop 0
	v_add_f32_e32 v44, 1.0, v44
	v_rcp_f32_e32 v44, v44
	s_nop 0
	v_mul_f32_e64 v44, v44, -v55
	v_mul_f32_e32 v45, 0x3fb8aa3b, v44
	v_exp_f32_e32 v178, v45
	v_add_f32_e32 v44, v44, v44
	v_cmp_nlt_f32_e32 vcc, s92, v44
	s_and_saveexec_b64 s[2:3], vcc
	s_xor_b64 s[2:3], exec, s[2:3]
	v_fma_f32 v184, v178, v178, -1.0
	s_andn2_saveexec_b64 s[2:3], s[2:3]
	v_fmamk_f32 v45, v44, 0x3c088888, v136
	v_fmaak_f32 v45, v44, v45, 0x3e2aaaab
	v_fma_f32 v45, v44, v45, 0.5
	v_fma_f32 v45, v44, v45, 1.0
	v_mul_f32_e32 v184, v44, v45
	s_or_b64 exec, exec, s[2:3]
	ds_read_b128 v[60:63], v115 offset:2688
	ds_read_b128 v[52:55], v115 offset:2704
	ds_read_b128 v[64:67], v115 offset:3200
	ds_read_b128 v[44:47], v115 offset:2944
	ds_read_b128 v[48:51], v115 offset:2960
	ds_read_b128 v[56:59], v115 offset:3216
	s_waitcnt lgkmcnt(0)
	v_add_f32_e32 v40, v40, v60
	v_mul_f32_e32 v40, 0xbfb8aa3b, v40
	v_exp_f32_e32 v40, v40
	s_nop 0
	v_add_f32_e32 v40, 1.0, v40
	v_rcp_f32_e32 v40, v40
	s_nop 0
	v_mul_f32_e64 v60, v40, -v64
	v_mul_f32_e32 v40, 0x3fb8aa3b, v60
	v_exp_f32_e32 v40, v40
	v_add_f32_e32 v60, v60, v60
	v_cmp_nlt_f32_e32 vcc, s92, v60
	s_and_saveexec_b64 s[2:3], vcc
	s_xor_b64 s[2:3], exec, s[2:3]
	v_fma_f32 v64, v40, v40, -1.0
	s_andn2_saveexec_b64 s[2:3], s[2:3]
	v_fmamk_f32 v64, v60, 0x3c088888, v136
	v_fmaak_f32 v64, v60, v64, 0x3e2aaaab
	v_fma_f32 v64, v60, v64, 0.5
	v_fma_f32 v64, v60, v64, 1.0
	v_mul_f32_e32 v64, v60, v64
	s_or_b64 exec, exec, s[2:3]
	v_add_f32_e32 v41, v41, v61
	v_mul_f32_e32 v41, 0xbfb8aa3b, v41
	v_exp_f32_e32 v41, v41
	s_nop 0
	v_add_f32_e32 v41, 1.0, v41
	v_rcp_f32_e32 v41, v41
	s_nop 0
	v_mul_f32_e64 v41, v41, -v65
	v_mul_f32_e32 v60, 0x3fb8aa3b, v41
	v_exp_f32_e32 v60, v60
	v_add_f32_e32 v61, v41, v41
	v_cmp_nlt_f32_e32 vcc, s92, v61
	s_and_saveexec_b64 s[2:3], vcc
	s_xor_b64 s[2:3], exec, s[2:3]
	v_fma_f32 v41, v60, v60, -1.0
	s_andn2_saveexec_b64 s[2:3], s[2:3]
	v_fmamk_f32 v41, v61, 0x3c088888, v136
	v_fmaak_f32 v41, v61, v41, 0x3e2aaaab
	v_fma_f32 v41, v61, v41, 0.5
	v_fma_f32 v41, v61, v41, 1.0
	v_mul_f32_e32 v41, v61, v41
	s_or_b64 exec, exec, s[2:3]
	v_add_f32_e32 v42, v42, v62
	v_mul_f32_e32 v42, 0xbfb8aa3b, v42
	v_exp_f32_e32 v42, v42
	s_nop 0
	v_add_f32_e32 v42, 1.0, v42
	v_rcp_f32_e32 v42, v42
	s_nop 0
	v_mul_f32_e64 v42, v42, -v66
	v_mul_f32_e32 v61, 0x3fb8aa3b, v42
	v_exp_f32_e32 v61, v61
	v_add_f32_e32 v62, v42, v42
	v_cmp_nlt_f32_e32 vcc, s92, v62
	s_and_saveexec_b64 s[2:3], vcc
	s_xor_b64 s[2:3], exec, s[2:3]
	v_fma_f32 v42, v61, v61, -1.0
	s_andn2_saveexec_b64 s[2:3], s[2:3]
	v_fmamk_f32 v42, v62, 0x3c088888, v136
; __device__ __forceinline__ float fsigmoid(float x) { return __builtin_amdgcn_rcpf(1.0f + __builtin_amdgcn_exp2f(-1.4426950408889634f * x)); }
; __device__ __forceinline__ void lru_item(const Frame& F, const bf16* XR, bf16* XGYL, const float* conv_w, const float* conv_b, const float* wa, const float* ba, const float* wx, const float* bx, const float* lam, int b, int hh, int j2) {
;     ...
;             for (int i = 0; i < 8; ++i) { const float bai = (i < 4) ? ba0[i & 3] : ba1[i & 3], bxi = (i < 4) ? bx0[i & 3] : bx1[i & 3], spi = (i < 4) ? sp0[i & 3] : sp1[i & 3];
;                 const float rp = pa[s2 * 2 + (i >> 2)][i & 3] + bai, xp = pa[4 + s2 * 2 + (i >> 2)][i & 3] + bxi;
;                 const float rr = pg8::fsigmoid(rp), ig = pg8::fsigmoid(xp), la = -spi * rr, x2 = 2.0f * la;
;                 const float a = __builtin_amdgcn_exp2f(LOG2E * la);
;                 const float em1 = (x2 > -0.3f) ? x2 * (1.0f + x2 * (0.5f + x2 * (0.16666667f + x2 * (0.041666668f + x2 * 0.0083333333f)))) : (a * a - 1.0f);
;                 av[8 * s2 + i] = a; uv[8 * s2 + i] = __builtin_amdgcn_sqrtf(-em1) * ig * xcf[8 * s2 + i]; } }
	v_fmaak_f32 v42, v62, v42, 0x3e2aaaab
	v_fma_f32 v42, v62, v42, 0.5
	v_fma_f32 v42, v62, v42, 1.0
	v_mul_f32_e32 v42, v62, v42
	s_or_b64 exec, exec, s[2:3]
	v_add_f32_e32 v43, v43, v63
	v_mul_f32_e32 v43, 0xbfb8aa3b, v43
	v_exp_f32_e32 v43, v43
	s_nop 0
	v_add_f32_e32 v43, 1.0, v43
	v_rcp_f32_e32 v43, v43
	s_nop 0
	v_mul_f32_e64 v43, v43, -v67
	v_mul_f32_e32 v62, 0x3fb8aa3b, v43
	v_exp_f32_e32 v62, v62
	v_add_f32_e32 v63, v43, v43
	v_cmp_nlt_f32_e32 vcc, s92, v63
	s_and_saveexec_b64 s[2:3], vcc
	s_xor_b64 s[2:3], exec, s[2:3]
	v_fma_f32 v43, v62, v62, -1.0
	s_andn2_saveexec_b64 s[2:3], s[2:3]
	v_fmamk_f32 v43, v63, 0x3c088888, v136
	v_fmaak_f32 v43, v63, v43, 0x3e2aaaab
	v_fma_f32 v43, v63, v43, 0.5
	v_fma_f32 v43, v63, v43, 1.0
	v_mul_f32_e32 v43, v63, v43
	s_or_b64 exec, exec, s[2:3]
	v_add_f32_e32 v28, v28, v52
	v_mul_f32_e32 v28, 0xbfb8aa3b, v28
	v_exp_f32_e32 v28, v28
	s_nop 0
	v_add_f32_e32 v28, 1.0, v28
	v_rcp_f32_e32 v28, v28
	s_nop 0
	v_mul_f32_e64 v52, v28, -v56
	v_mul_f32_e32 v28, 0x3fb8aa3b, v52
	v_exp_f32_e32 v28, v28
	v_add_f32_e32 v52, v52, v52
	v_cmp_nlt_f32_e32 vcc, s92, v52
	s_and_saveexec_b64 s[2:3], vcc
	s_xor_b64 s[2:3], exec, s[2:3]
	v_fma_f32 v56, v28, v28, -1.0
	s_andn2_saveexec_b64 s[2:3], s[2:3]
	v_fmamk_f32 v56, v52, 0x3c088888, v136
	v_fmaak_f32 v56, v52, v56, 0x3e2aaaab
	v_fma_f32 v56, v52, v56, 0.5
	v_fma_f32 v56, v52, v56, 1.0
	v_mul_f32_e32 v56, v52, v56
	s_or_b64 exec, exec, s[2:3]
	v_add_f32_e32 v29, v29, v53
	v_mul_f32_e32 v29, 0xbfb8aa3b, v29
	v_exp_f32_e32 v29, v29
	s_nop 0
	v_add_f32_e32 v29, 1.0, v29
	v_rcp_f32_e32 v29, v29
	s_nop 0
	v_mul_f32_e64 v29, v29, -v57
	v_mul_f32_e32 v52, 0x3fb8aa3b, v29
	v_exp_f32_e32 v52, v52
	v_add_f32_e32 v53, v29, v29
	v_cmp_nlt_f32_e32 vcc, s92, v53
	s_and_saveexec_b64 s[2:3], vcc
	s_xor_b64 s[2:3], exec, s[2:3]
	v_fma_f32 v29, v52, v52, -1.0
	s_andn2_saveexec_b64 s[2:3], s[2:3]
	v_fmamk_f32 v29, v53, 0x3c088888, v136
	v_fmaak_f32 v29, v53, v29, 0x3e2aaaab
	v_fma_f32 v29, v53, v29, 0.5
	v_fma_f32 v29, v53, v29, 1.0
	v_mul_f32_e32 v29, v53, v29
	s_or_b64 exec, exec, s[2:3]
	v_add_f32_e32 v30, v30, v54
	v_mul_f32_e32 v30, 0xbfb8aa3b, v30
	v_exp_f32_e32 v30, v30
	s_nop 0
	v_add_f32_e32 v30, 1.0, v30
	v_rcp_f32_e32 v30, v30
	s_nop 0
	v_mul_f32_e64 v30, v30, -v58
	v_mul_f32_e32 v53, 0x3fb8aa3b, v30
	v_exp_f32_e32 v53, v53
	v_add_f32_e32 v30, v30, v30
	v_cmp_nlt_f32_e32 vcc, s92, v30
	s_and_saveexec_b64 s[2:3], vcc
	s_xor_b64 s[2:3], exec, s[2:3]
	v_fma_f32 v57, v53, v53, -1.0
	s_andn2_saveexec_b64 s[2:3], s[2:3]
	v_fmamk_f32 v54, v30, 0x3c088888, v136
	v_fmaak_f32 v54, v30, v54, 0x3e2aaaab
	v_fma_f32 v54, v30, v54, 0.5
	v_fma_f32 v54, v30, v54, 1.0
	v_mul_f32_e32 v57, v30, v54
	s_or_b64 exec, exec, s[2:3]
	v_add_f32_e32 v30, v31, v55
	v_mul_f32_e32 v30, 0xbfb8aa3b, v30
	v_exp_f32_e32 v30, v30
	s_nop 0
	v_add_f32_e32 v30, 1.0, v30
	v_rcp_f32_e32 v30, v30
	s_nop 0
	v_mul_f32_e64 v30, v30, -v59
	v_mul_f32_e32 v31, 0x3fb8aa3b, v30
	v_exp_f32_e32 v54, v31
	v_add_f32_e32 v31, v30, v30
	v_cmp_nlt_f32_e32 vcc, s92, v31
	s_and_saveexec_b64 s[2:3], vcc
	s_xor_b64 s[2:3], exec, s[2:3]
	v_fma_f32 v30, v54, v54, -1.0
	s_andn2_saveexec_b64 s[2:3], s[2:3]
	v_fmamk_f32 v30, v31, 0x3c088888, v136
	v_fmaak_f32 v30, v31, v30, 0x3e2aaaab
	v_fma_f32 v30, v31, v30, 0.5
	v_fma_f32 v30, v31, v30, 1.0
	v_mul_f32_e32 v30, v31, v30
	s_or_b64 exec, exec, s[2:3]
	v_add_f32_e32 v18, v18, v50
	v_mul_f32_e32 v18, 0xbfb8aa3b, v18
	v_exp_f32_e32 v18, v18
	v_add_f32_e32 v19, v19, v51
	v_add_f32_e32 v17, v17, v49
	v_mul_f32_e32 v19, 0xbfb8aa3b, v19
	v_add_f32_e32 v18, 1.0, v18
	v_mul_f32_e32 v17, 0xbfb8aa3b, v17
	v_sqrt_f32_e64 v50, -v57
	v_rcp_f32_e32 v18, v18
	v_exp_f32_e32 v19, v19
	v_exp_f32_e32 v49, v17
	v_add_f32_e32 v16, v16, v48
	v_mul_f32_e32 v16, 0xbfb8aa3b, v16
	v_mul_f32_e32 v17, v18, v50
	v_add_f32_e32 v18, 1.0, v19
	v_add_f32_e32 v19, 1.0, v49
	v_exp_f32_e32 v16, v16
	v_rcp_f32_e32 v19, v19
	v_sqrt_f32_e64 v29, -v29
	v_add_f32_e32 v35, v35, v47
	v_add_f32_e32 v16, 1.0, v16
	v_mul_f32_e32 v35, 0xbfb8aa3b, v35
	v_mul_f32_e32 v19, v19, v29
	v_rcp_f32_e32 v16, v16
	v_sqrt_f32_e64 v29, -v56
	v_exp_f32_e32 v35, v35
	v_add_f32_e32 v33, v33, v45
	v_mul_f32_e32 v33, 0xbfb8aa3b, v33
	v_mul_f32_e32 v16, v16, v29
	v_add_f32_e32 v29, 1.0, v35
	v_rcp_f32_e32 v35, v29
	v_add_f32_e32 v29, v34, v46
	v_mul_f32_e32 v29, 0xbfb8aa3b, v29
	v_exp_f32_e32 v34, v29
	v_sqrt_f32_e64 v43, -v43
	v_exp_f32_e32 v33, v33
	v_cndmask_b32_e64 v31, v168, v150, s[42:43]
	v_add_f32_e32 v34, 1.0, v34
	v_rcp_f32_e32 v34, v34
	v_sqrt_f32_e64 v42, -v42
	v_mul_f32_e32 v17, v31, v17
	v_cndmask_b32_e64 v31, v167, v149, s[42:43]
	v_add_f32_e32 v32, v32, v44
	v_mul_f32_e32 v31, v31, v19
	v_cndmask_b32_e64 v19, v166, v148, s[42:43]
	v_mul_f32_e32 v32, 0xbfb8aa3b, v32
	v_mul_f32_e32 v29, v19, v16
	v_cndmask_b32_e64 v16, v165, v147, s[42:43]
	v_mul_f32_e32 v19, v35, v43
	v_add_f32_e32 v33, 1.0, v33
	v_exp_f32_e32 v32, v32
	v_mul_f32_e32 v35, v16, v19
	v_mul_f32_e32 v19, v34, v42
	v_rcp_f32_e32 v34, v33
	v_sqrt_f32_e64 v41, -v41
	v_add_f32_e32 v27, v27, v39
	v_mul_f32_e32 v27, 0xbfb8aa3b, v27
	v_cndmask_b32_e64 v16, v164, v146, s[42:43]
	v_add_f32_e32 v32, 1.0, v32
	v_exp_f32_e32 v27, v27
	v_mul_f32_e32 v33, v16, v19
	v_mul_f32_e32 v19, v34, v41
	v_rcp_f32_e32 v32, v32
	v_sqrt_f32_e64 v34, -v64
	v_add_f32_e32 v26, v26, v38
	v_mul_f32_e32 v26, 0xbfb8aa3b, v26
	v_cndmask_b32_e64 v16, v163, v145, s[42:43]
	v_add_f32_e32 v27, 1.0, v27
	v_exp_f32_e32 v26, v26
	v_mul_f32_e32 v41, v16, v19
	v_mul_f32_e32 v19, v32, v34
	v_rcp_f32_e32 v27, v27
	v_sqrt_f32_e64 v32, -v184
	v_add_f32_e32 v25, v25, v37
	v_mul_f32_e32 v25, 0xbfb8aa3b, v25
; __device__ __forceinline__ float fsigmoid(float x) { return __builtin_amdgcn_rcpf(1.0f + __builtin_amdgcn_exp2f(-1.4426950408889634f * x)); }
; __device__ __forceinline__ void lru_item(const Frame& F, const bf16* XR, bf16* XGYL, const float* conv_w, const float* conv_b, const float* wa, const float* ba, const float* wx, const float* bx, const float* lam, int b, int hh, int j2) {
;     ...
;                 const float rr = pg8::fsigmoid(rp), ig = pg8::fsigmoid(xp), la = -spi * rr, x2 = 2.0f * la;
;                 const float a = __builtin_amdgcn_exp2f(LOG2E * la);
;                 const float em1 = (x2 > -0.3f) ? x2 * (1.0f + x2 * (0.5f + x2 * (0.16666667f + x2 * (0.041666668f + x2 * 0.0083333333f)))) : (a * a - 1.0f);
;                 av[8 * s2 + i] = a; uv[8 * s2 + i] = __builtin_amdgcn_sqrtf(-em1) * ig * xcf[8 * s2 + i]; } }
; #pragma unroll
;         for (int i = 0; i < 16; ++i) {
;             { const float ap = row_shr<1>(1.0f, av[i]), up = row_shr<1>(0.0f, uv[i]); uv[i] = fmaf(av[i], up, uv[i]); av[i] *= ap; }
;             { const float ap = row_shr<2>(1.0f, av[i]), up = row_shr<2>(0.0f, uv[i]); uv[i] = fmaf(av[i], up, uv[i]); av[i] *= ap; }
;             { const float ap = row_shr<4>(1.0f, av[i]), up = row_shr<4>(0.0f, uv[i]); uv[i] = fmaf(av[i], up, uv[i]); av[i] *= ap; }
	v_cndmask_b32_e64 v16, v162, v144, s[42:43]
	v_add_f32_e32 v26, 1.0, v26
	v_exp_f32_e32 v25, v25
	v_mul_f32_e32 v39, v16, v19
	v_mul_f32_e32 v19, v27, v32
	v_rcp_f32_e32 v26, v26
	v_sqrt_f32_e64 v32, -v183
	v_add_f32_e32 v24, v24, v36
	v_mul_f32_e32 v24, 0xbfb8aa3b, v24
	v_cndmask_b32_e64 v16, v160, v142, s[42:43]
	v_add_f32_e32 v25, 1.0, v25
	v_exp_f32_e32 v24, v24
	v_mul_f32_e32 v27, v16, v19
	v_mul_f32_e32 v19, v26, v32
	v_rcp_f32_e32 v26, v25
	v_sqrt_f32_e64 v32, -v182
	v_add_f32_e32 v15, v23, v15
	v_mul_f32_e32 v15, 0xbfb8aa3b, v15
	v_add_f32_e32 v14, v22, v14
	v_cndmask_b32_e64 v16, v159, v141, s[42:43]
	v_add_f32_e32 v24, 1.0, v24
	v_exp_f32_e32 v15, v15
	v_mul_f32_e32 v14, 0xbfb8aa3b, v14
	v_mul_f32_e32 v25, v16, v19
	v_mul_f32_e32 v19, v26, v32
	v_rcp_f32_e32 v24, v24
	v_sqrt_f32_e64 v26, -v181
	v_exp_f32_e32 v14, v14
	v_add_f32_e32 v13, v21, v13
	v_cndmask_b32_e64 v16, v158, v140, s[42:43]
	v_add_f32_e32 v15, 1.0, v15
	v_mul_f32_e32 v13, 0xbfb8aa3b, v13
	v_mul_f32_e32 v45, v16, v19
	v_cndmask_b32_e64 v16, v155, v95, s[42:43]
	v_mul_f32_e32 v19, v24, v26
	v_rcp_f32_e32 v15, v15
	v_sqrt_f32_e64 v23, -v180
	v_add_f32_e32 v14, 1.0, v14
	v_exp_f32_e32 v13, v13
	v_mul_f32_e32 v43, v16, v19
	v_rcp_f32_e32 v14, v14
	v_sqrt_f32_e64 v19, -v179
	v_add_f32_e32 v12, v20, v12
	v_mul_f32_e32 v12, 0xbfb8aa3b, v12
	v_cndmask_b32_e64 v16, v154, v93, s[42:43]
	v_mul_f32_e32 v15, v15, v23
	v_add_f32_e32 v13, 1.0, v13
	v_exp_f32_e32 v12, v12
	v_mul_f32_e32 v15, v16, v15
	v_mul_f32_e32 v14, v14, v19
	v_rcp_f32_e32 v16, v13
	v_sqrt_f32_e64 v19, -v176
	v_cndmask_b32_e64 v2, v153, v2, s[42:43]
	v_add_f32_e32 v12, 1.0, v12
	v_mul_f32_e32 v13, v2, v14
	v_cndmask_b32_e64 v1, v152, v1, s[42:43]
	v_mul_f32_e32 v2, v16, v19
	v_rcp_f32_e32 v12, v12
	v_sqrt_f32_e64 v14, -v171
	v_rcp_f32_e32 v18, v18
	v_mul_f32_e32 v23, v1, v2
	v_sqrt_f32_e64 v1, -v30
	v_cndmask_b32_e64 v0, v151, v0, s[42:43]
	v_mul_f32_e32 v2, v12, v14
	v_mul_f32_e32 v21, v0, v2
	v_cndmask_b32_e64 v0, v161, v143, s[42:43]
	v_mul_f32_e32 v1, v18, v1
	v_mul_f32_e32 v19, v0, v1
	s_lshl_b32 s2, s7, 12
	s_add_i32 s7, s2, 0
	v_mov_b32_e32 v20, v169
	v_mov_b32_e32 v22, v170
	v_mov_b32_e32 v12, v172
	v_mov_b32_e32 v14, v173
	v_mov_b32_e32 v42, v174
	v_mov_b32_e32 v44, v175
	v_mov_b32_e32 v24, v177
	v_mov_b32_e32 v26, v178
	v_mov_b32_e32 v38, v40
	v_mov_b32_e32 v40, v60
	v_mov_b32_e32 v32, v61
	v_mov_b32_e32 v34, v62
	v_mov_b32_e32 v28, v28
	v_mov_b32_e32 v30, v52
	v_mov_b32_e32 v16, v53
	v_mov_b32_e32 v18, v54
	v_fmac_f32_dpp v21, v21, v20 row_shr:1 row_mask:0xf bank_mask:0xf
	v_fmac_f32_dpp v23, v23, v22 row_shr:1 row_mask:0xf bank_mask:0xf
	v_fmac_f32_dpp v13, v13, v12 row_shr:1 row_mask:0xf bank_mask:0xf
	v_fmac_f32_dpp v15, v15, v14 row_shr:1 row_mask:0xf bank_mask:0xf
	v_fmac_f32_dpp v43, v43, v42 row_shr:1 row_mask:0xf bank_mask:0xf
	v_fmac_f32_dpp v45, v45, v44 row_shr:1 row_mask:0xf bank_mask:0xf
	v_fmac_f32_dpp v25, v25, v24 row_shr:1 row_mask:0xf bank_mask:0xf
	v_fmac_f32_dpp v27, v27, v26 row_shr:1 row_mask:0xf bank_mask:0xf
	v_fmac_f32_dpp v39, v39, v38 row_shr:1 row_mask:0xf bank_mask:0xf
	v_fmac_f32_dpp v41, v41, v40 row_shr:1 row_mask:0xf bank_mask:0xf
	v_fmac_f32_dpp v33, v33, v32 row_shr:1 row_mask:0xf bank_mask:0xf
	v_fmac_f32_dpp v35, v35, v34 row_shr:1 row_mask:0xf bank_mask:0xf
	v_fmac_f32_dpp v29, v29, v28 row_shr:1 row_mask:0xf bank_mask:0xf
	v_fmac_f32_dpp v31, v31, v30 row_shr:1 row_mask:0xf bank_mask:0xf
	v_fmac_f32_dpp v17, v17, v16 row_shr:1 row_mask:0xf bank_mask:0xf
	v_fmac_f32_dpp v19, v19, v18 row_shr:1 row_mask:0xf bank_mask:0xf
	v_mul_f32_dpp v20, v20, v20 row_shr:1 row_mask:0xf bank_mask:0xf
	v_mul_f32_dpp v22, v22, v22 row_shr:1 row_mask:0xf bank_mask:0xf
	v_mul_f32_dpp v12, v12, v12 row_shr:1 row_mask:0xf bank_mask:0xf
	v_mul_f32_dpp v14, v14, v14 row_shr:1 row_mask:0xf bank_mask:0xf
	v_mul_f32_dpp v42, v42, v42 row_shr:1 row_mask:0xf bank_mask:0xf
	v_mul_f32_dpp v44, v44, v44 row_shr:1 row_mask:0xf bank_mask:0xf
	v_mul_f32_dpp v24, v24, v24 row_shr:1 row_mask:0xf bank_mask:0xf
	v_mul_f32_dpp v26, v26, v26 row_shr:1 row_mask:0xf bank_mask:0xf
	v_mul_f32_dpp v38, v38, v38 row_shr:1 row_mask:0xf bank_mask:0xf
	v_mul_f32_dpp v40, v40, v40 row_shr:1 row_mask:0xf bank_mask:0xf
	v_mul_f32_dpp v32, v32, v32 row_shr:1 row_mask:0xf bank_mask:0xf
	v_mul_f32_dpp v34, v34, v34 row_shr:1 row_mask:0xf bank_mask:0xf
	v_mul_f32_dpp v28, v28, v28 row_shr:1 row_mask:0xf bank_mask:0xf
	v_mul_f32_dpp v30, v30, v30 row_shr:1 row_mask:0xf bank_mask:0xf
	v_mul_f32_dpp v16, v16, v16 row_shr:1 row_mask:0xf bank_mask:0xf
	v_mul_f32_dpp v18, v18, v18 row_shr:1 row_mask:0xf bank_mask:0xf
	v_fmac_f32_dpp v21, v21, v20 row_shr:2 row_mask:0xf bank_mask:0xf
	v_fmac_f32_dpp v23, v23, v22 row_shr:2 row_mask:0xf bank_mask:0xf
	v_fmac_f32_dpp v13, v13, v12 row_shr:2 row_mask:0xf bank_mask:0xf
	v_fmac_f32_dpp v15, v15, v14 row_shr:2 row_mask:0xf bank_mask:0xf
	v_fmac_f32_dpp v43, v43, v42 row_shr:2 row_mask:0xf bank_mask:0xf
	v_fmac_f32_dpp v45, v45, v44 row_shr:2 row_mask:0xf bank_mask:0xf
	v_fmac_f32_dpp v25, v25, v24 row_shr:2 row_mask:0xf bank_mask:0xf
	v_fmac_f32_dpp v27, v27, v26 row_shr:2 row_mask:0xf bank_mask:0xf
	v_fmac_f32_dpp v39, v39, v38 row_shr:2 row_mask:0xf bank_mask:0xf
	v_fmac_f32_dpp v41, v41, v40 row_shr:2 row_mask:0xf bank_mask:0xf
	v_fmac_f32_dpp v33, v33, v32 row_shr:2 row_mask:0xf bank_mask:0xf
	v_fmac_f32_dpp v35, v35, v34 row_shr:2 row_mask:0xf bank_mask:0xf
	v_fmac_f32_dpp v29, v29, v28 row_shr:2 row_mask:0xf bank_mask:0xf
	v_fmac_f32_dpp v31, v31, v30 row_shr:2 row_mask:0xf bank_mask:0xf
	v_fmac_f32_dpp v17, v17, v16 row_shr:2 row_mask:0xf bank_mask:0xf
; #define LAS __attribute__((address_space(3)))
; __device__ __forceinline__ void lru_item(const Frame& F, const bf16* XR, bf16* XGYL, const float* conv_w, const float* conv_b, const float* wa, const float* ba, const float* wx, const float* bx, const float* lam, int b, int hh, int j2) {
;     ...
; #pragma unroll
;         for (int i = 0; i < 16; ++i) {
;             { const float ap = row_shr<1>(1.0f, av[i]), up = row_shr<1>(0.0f, uv[i]); uv[i] = fmaf(av[i], up, uv[i]); av[i] *= ap; }
;             { const float ap = row_shr<2>(1.0f, av[i]), up = row_shr<2>(0.0f, uv[i]); uv[i] = fmaf(av[i], up, uv[i]); av[i] *= ap; }
;             { const float ap = row_shr<4>(1.0f, av[i]), up = row_shr<4>(0.0f, uv[i]); uv[i] = fmaf(av[i], up, uv[i]); av[i] *= ap; }
;             { const float ap = row_shr<8>(1.0f, av[i]), up = row_shr<8>(0.0f, uv[i]); uv[i] = fmaf(av[i], up, uv[i]); av[i] *= ap; } }
;         LAS float* tb = tot + (chunk & 1) * 1024;
;         if (tl == 15) {
; #pragma unroll
;             for (int i = 0; i < 16; i += 2) *(LAS f32x4*)(tb + (w * 64 + g * 16 + i) * 2) = (f32x4){av[i], uv[i], av[i + 1], uv[i + 1]}; }
	v_fmac_f32_dpp v19, v19, v18 row_shr:2 row_mask:0xf bank_mask:0xf
	v_mul_f32_dpp v20, v20, v20 row_shr:2 row_mask:0xf bank_mask:0xf
	v_mul_f32_dpp v22, v22, v22 row_shr:2 row_mask:0xf bank_mask:0xf
	v_mul_f32_dpp v12, v12, v12 row_shr:2 row_mask:0xf bank_mask:0xf
	v_mul_f32_dpp v14, v14, v14 row_shr:2 row_mask:0xf bank_mask:0xf
	v_mul_f32_dpp v42, v42, v42 row_shr:2 row_mask:0xf bank_mask:0xf
	v_mul_f32_dpp v44, v44, v44 row_shr:2 row_mask:0xf bank_mask:0xf
	v_mul_f32_dpp v24, v24, v24 row_shr:2 row_mask:0xf bank_mask:0xf
	v_mul_f32_dpp v26, v26, v26 row_shr:2 row_mask:0xf bank_mask:0xf
	v_mul_f32_dpp v38, v38, v38 row_shr:2 row_mask:0xf bank_mask:0xf
	v_mul_f32_dpp v40, v40, v40 row_shr:2 row_mask:0xf bank_mask:0xf
	v_mul_f32_dpp v32, v32, v32 row_shr:2 row_mask:0xf bank_mask:0xf
	v_mul_f32_dpp v34, v34, v34 row_shr:2 row_mask:0xf bank_mask:0xf
	v_mul_f32_dpp v28, v28, v28 row_shr:2 row_mask:0xf bank_mask:0xf
	v_mul_f32_dpp v30, v30, v30 row_shr:2 row_mask:0xf bank_mask:0xf
	v_mul_f32_dpp v16, v16, v16 row_shr:2 row_mask:0xf bank_mask:0xf
	v_mul_f32_dpp v18, v18, v18 row_shr:2 row_mask:0xf bank_mask:0xf
	v_fmac_f32_dpp v21, v21, v20 row_shr:4 row_mask:0xf bank_mask:0xf
	v_fmac_f32_dpp v23, v23, v22 row_shr:4 row_mask:0xf bank_mask:0xf
	v_fmac_f32_dpp v13, v13, v12 row_shr:4 row_mask:0xf bank_mask:0xf
	v_fmac_f32_dpp v15, v15, v14 row_shr:4 row_mask:0xf bank_mask:0xf
	v_fmac_f32_dpp v43, v43, v42 row_shr:4 row_mask:0xf bank_mask:0xf
	v_fmac_f32_dpp v45, v45, v44 row_shr:4 row_mask:0xf bank_mask:0xf
	v_fmac_f32_dpp v25, v25, v24 row_shr:4 row_mask:0xf bank_mask:0xf
	v_fmac_f32_dpp v27, v27, v26 row_shr:4 row_mask:0xf bank_mask:0xf
	v_fmac_f32_dpp v39, v39, v38 row_shr:4 row_mask:0xf bank_mask:0xf
	v_fmac_f32_dpp v41, v41, v40 row_shr:4 row_mask:0xf bank_mask:0xf
	v_fmac_f32_dpp v33, v33, v32 row_shr:4 row_mask:0xf bank_mask:0xf
	v_fmac_f32_dpp v35, v35, v34 row_shr:4 row_mask:0xf bank_mask:0xf
	v_fmac_f32_dpp v29, v29, v28 row_shr:4 row_mask:0xf bank_mask:0xf
	v_fmac_f32_dpp v31, v31, v30 row_shr:4 row_mask:0xf bank_mask:0xf
	v_fmac_f32_dpp v17, v17, v16 row_shr:4 row_mask:0xf bank_mask:0xf
	v_fmac_f32_dpp v19, v19, v18 row_shr:4 row_mask:0xf bank_mask:0xf
	v_mul_f32_dpp v20, v20, v20 row_shr:4 row_mask:0xf bank_mask:0xf
	v_mul_f32_dpp v22, v22, v22 row_shr:4 row_mask:0xf bank_mask:0xf
	v_mul_f32_dpp v12, v12, v12 row_shr:4 row_mask:0xf bank_mask:0xf
	v_mul_f32_dpp v14, v14, v14 row_shr:4 row_mask:0xf bank_mask:0xf
	v_mul_f32_dpp v42, v42, v42 row_shr:4 row_mask:0xf bank_mask:0xf
	v_mul_f32_dpp v44, v44, v44 row_shr:4 row_mask:0xf bank_mask:0xf
	v_mul_f32_dpp v24, v24, v24 row_shr:4 row_mask:0xf bank_mask:0xf
	v_mul_f32_dpp v26, v26, v26 row_shr:4 row_mask:0xf bank_mask:0xf
	v_mul_f32_dpp v38, v38, v38 row_shr:4 row_mask:0xf bank_mask:0xf
	v_mul_f32_dpp v40, v40, v40 row_shr:4 row_mask:0xf bank_mask:0xf
	v_mul_f32_dpp v32, v32, v32 row_shr:4 row_mask:0xf bank_mask:0xf
	v_mul_f32_dpp v34, v34, v34 row_shr:4 row_mask:0xf bank_mask:0xf
	v_mul_f32_dpp v28, v28, v28 row_shr:4 row_mask:0xf bank_mask:0xf
	v_mul_f32_dpp v30, v30, v30 row_shr:4 row_mask:0xf bank_mask:0xf
	v_mul_f32_dpp v16, v16, v16 row_shr:4 row_mask:0xf bank_mask:0xf
	v_mul_f32_dpp v18, v18, v18 row_shr:4 row_mask:0xf bank_mask:0xf
	v_fmac_f32_dpp v21, v21, v20 row_shr:8 row_mask:0xf bank_mask:0xf
	v_fmac_f32_dpp v23, v23, v22 row_shr:8 row_mask:0xf bank_mask:0xf
	v_fmac_f32_dpp v13, v13, v12 row_shr:8 row_mask:0xf bank_mask:0xf
	v_fmac_f32_dpp v15, v15, v14 row_shr:8 row_mask:0xf bank_mask:0xf
	v_fmac_f32_dpp v43, v43, v42 row_shr:8 row_mask:0xf bank_mask:0xf
	v_fmac_f32_dpp v45, v45, v44 row_shr:8 row_mask:0xf bank_mask:0xf
	v_fmac_f32_dpp v25, v25, v24 row_shr:8 row_mask:0xf bank_mask:0xf
	v_fmac_f32_dpp v27, v27, v26 row_shr:8 row_mask:0xf bank_mask:0xf
	v_fmac_f32_dpp v39, v39, v38 row_shr:8 row_mask:0xf bank_mask:0xf
	v_fmac_f32_dpp v41, v41, v40 row_shr:8 row_mask:0xf bank_mask:0xf
	v_fmac_f32_dpp v33, v33, v32 row_shr:8 row_mask:0xf bank_mask:0xf
	v_fmac_f32_dpp v35, v35, v34 row_shr:8 row_mask:0xf bank_mask:0xf
	v_fmac_f32_dpp v29, v29, v28 row_shr:8 row_mask:0xf bank_mask:0xf
	v_fmac_f32_dpp v31, v31, v30 row_shr:8 row_mask:0xf bank_mask:0xf
	v_fmac_f32_dpp v17, v17, v16 row_shr:8 row_mask:0xf bank_mask:0xf
	v_fmac_f32_dpp v19, v19, v18 row_shr:8 row_mask:0xf bank_mask:0xf
	v_mul_f32_dpp v20, v20, v20 row_shr:8 row_mask:0xf bank_mask:0xf
	v_mul_f32_dpp v22, v22, v22 row_shr:8 row_mask:0xf bank_mask:0xf
	v_mul_f32_dpp v12, v12, v12 row_shr:8 row_mask:0xf bank_mask:0xf
	v_mul_f32_dpp v14, v14, v14 row_shr:8 row_mask:0xf bank_mask:0xf
	v_mul_f32_dpp v42, v42, v42 row_shr:8 row_mask:0xf bank_mask:0xf
	v_mul_f32_dpp v44, v44, v44 row_shr:8 row_mask:0xf bank_mask:0xf
	v_mul_f32_dpp v24, v24, v24 row_shr:8 row_mask:0xf bank_mask:0xf
	v_mul_f32_dpp v26, v26, v26 row_shr:8 row_mask:0xf bank_mask:0xf
	v_mul_f32_dpp v38, v38, v38 row_shr:8 row_mask:0xf bank_mask:0xf
	v_mul_f32_dpp v40, v40, v40 row_shr:8 row_mask:0xf bank_mask:0xf
	v_mul_f32_dpp v32, v32, v32 row_shr:8 row_mask:0xf bank_mask:0xf
	v_mul_f32_dpp v34, v34, v34 row_shr:8 row_mask:0xf bank_mask:0xf
	v_mul_f32_dpp v28, v28, v28 row_shr:8 row_mask:0xf bank_mask:0xf
	v_mul_f32_dpp v30, v30, v30 row_shr:8 row_mask:0xf bank_mask:0xf
	v_mul_f32_dpp v16, v16, v16 row_shr:8 row_mask:0xf bank_mask:0xf
	v_mul_f32_dpp v18, v18, v18 row_shr:8 row_mask:0xf bank_mask:0xf
	s_nop 1
	s_and_saveexec_b64 s[2:3], s[10:11]
	s_cbranch_execz .LBB0_338
	v_add_u32_e32 v0, s7, v132
	ds_write_b128 v0, v[20:23] offset:4096
	ds_write_b128 v0, v[12:15] offset:4112
	ds_write_b128 v0, v[42:45] offset:4128
	ds_write_b128 v0, v[24:27] offset:4144
	ds_write_b128 v0, v[38:41] offset:4160
	ds_write_b128 v0, v[32:35] offset:4176
	ds_write_b128 v0, v[28:31] offset:4192
	ds_write_b128 v0, v[16:19] offset:4208
	s_branch .LBB0_338
